# v18 plus NA bias gathers addressed from one unclamped base with immediate offsets (15 fewer VALU ops per key block)
# speedup vs baseline: 1.0049x; 1.0023x over previous
.LBB0_246:
	s_or_b64 exec, exec, s[0:1]
	v_lshrrev_b32_e32 v0, 3, v69
	v_and_b32_e32 v1, 4, v69
	v_and_or_b32 v0, v0, 56, v1
	v_lshrrev_b32_e32 v0, 1, v0
	v_or_b32_e32 v77, v0, v92
	v_lshlrev_b32_e32 v1, 4, v69
	v_sub_u32_e64 v2, v0, 4 clamp
	v_sub_u32_e64 v0, v0, 3 clamp
	v_and_b32_e32 v36, 48, v1
	v_ashrrev_i32_e32 v35, 9, v69
	v_min_u32_e32 v96, 24, v2
	v_min_u32_e32 v0, 24, v0
	v_or_b32_e32 v32, v36, v93
	v_lshlrev_b32_e32 v1, 6, v77
	v_lshlrev_b32_e32 v34, 11, v35
	v_sub_u32_e32 v0, v0, v96
	v_or3_b32 v80, v1, v34, v32
	v_lshlrev_b32_e32 v1, 6, v33
	v_add_u32_e32 v97, 8, v0
	v_mov_b32_e32 v15, 0
	v_ashrrev_i32_e32 v81, 31, v80
	v_cmp_lt_i32_e32 vcc, 0, v97
	v_lshlrev_b32_e32 v82, 1, v1
	v_mov_b32_e32 v14, v15
	v_mov_b32_e32 v13, v15
	v_mov_b32_e32 v12, v15
	v_mov_b32_e32 v11, v15
	v_mov_b32_e32 v10, v15
	v_mov_b32_e32 v9, v15
	v_mov_b32_e32 v8, v15
	v_mov_b32_e32 v7, v15
	v_mov_b32_e32 v6, v15
	v_mov_b32_e32 v5, v15
	v_mov_b32_e32 v4, v15
	v_mov_b32_e32 v3, v15
	v_mov_b32_e32 v2, v15
	v_mov_b32_e32 v1, v15
	v_mov_b32_e32 v0, v15
	v_mov_b32_e32 v31, v15
	v_mov_b32_e32 v30, v15
	v_mov_b32_e32 v29, v15
	v_mov_b32_e32 v28, v15
	v_mov_b32_e32 v27, v15
	v_mov_b32_e32 v26, v15
	v_mov_b32_e32 v25, v15
	v_mov_b32_e32 v24, v15
	v_mov_b32_e32 v23, v15
	v_mov_b32_e32 v22, v15
	v_mov_b32_e32 v21, v15
	v_mov_b32_e32 v20, v15
	v_mov_b32_e32 v19, v15
	v_mov_b32_e32 v18, v15
	v_mov_b32_e32 v17, v15
	v_mov_b32_e32 v16, v15
	v_mov_b32_e32 v117, v15
	s_waitcnt lgkmcnt(0)
	s_and_saveexec_b64 s[2:3], vcc
	s_cbranch_execz .LBB0_243
	v_writelane_b32 v254, s2, 57
	v_max_i32_e32 v0, 4, v77
	v_add_u32_e32 v3, -4, v0
	v_writelane_b32 v254, s3, 58
	v_writelane_b32 v254, s16, 59
	v_mov_b32_e32 v83, v65
	v_mov_b32_e32 v75, v65
	v_writelane_b32 v254, s17, 60
	v_sub_u32_e64 v2, v36, 8 clamp
	v_readlane_b32 s0, v254, 49
	v_readlane_b32 s1, v254, 50
	v_min_u32_e32 v98, 24, v3
	v_mov_b32_e32 v117, 0
	v_mov_b64_e32 v[0:1], s[0:1]
	v_mad_i64_i32 v[0:1], s[0:1], v80, s89, v[0:1]
	v_lshl_add_u64 v[0:1], v[0:1], 0, v[82:83]
	v_lshl_add_u64 v[0:1], v[0:1], 0, v[74:75]
	global_load_dwordx4 v[48:51], v[0:1], off
	global_load_dwordx4 v[52:55], v[0:1], off offset:32
	global_load_dwordx4 v[56:59], v[0:1], off offset:64
	global_load_dwordx4 v[60:63], v[0:1], off offset:96
	v_min_u32_e32 v75, 32, v2
	v_or_b32_e32 v4, v75, v68
	v_max_i32_e32 v2, 8, v32
	v_sub_u32_e32 v5, v4, v32
	v_add_u32_e32 v161, 15, v5
	v_add_u32_e32 v2, -8, v2
	v_max_i32_e32 v5, -15, v5
	v_min_u32_e32 v2, 48, v2
	v_add_u32_e32 v5, 15, v5
	v_add_u32_e32 v3, 16, v2
	v_min_u32_e32 v101, 30, v5
	v_or_b32_e32 v5, 1, v4
	v_cmp_ge_u32_e64 s[6:7], v5, v2
	v_cmp_lt_u32_e64 s[8:9], v5, v3
	v_sub_u32_e32 v5, v5, v32
	v_max_i32_e32 v5, -15, v5
	v_add_u32_e32 v5, 15, v5
	v_min_u32_e32 v102, 30, v5
	v_or_b32_e32 v5, 2, v4
	v_cmp_ge_u32_e64 s[10:11], v5, v2
	v_cmp_lt_u32_e64 s[12:13], v5, v3
	v_sub_u32_e32 v5, v5, v32
	v_max_i32_e32 v5, -15, v5
	v_add_u32_e32 v5, 15, v5
	v_min_u32_e32 v103, 30, v5
	v_or_b32_e32 v5, 3, v4
	v_cmp_ge_u32_e64 s[14:15], v5, v2
	v_cmp_lt_u32_e64 s[16:17], v5, v3
	v_sub_u32_e32 v5, v5, v32
	v_max_i32_e32 v5, -15, v5
	v_add_u32_e32 v5, 15, v5
	v_min_u32_e32 v104, 30, v5
	v_add_u32_e32 v5, 8, v4
	v_cmp_ge_u32_e64 s[18:19], v5, v2
	v_cmp_lt_u32_e64 s[20:21], v5, v3
	v_sub_u32_e32 v5, v5, v32
	v_max_i32_e32 v5, -15, v5
	v_add_u32_e32 v5, 15, v5
	v_min_u32_e32 v105, 30, v5
	v_add_u32_e32 v5, 9, v4
	v_cmp_ge_u32_e64 s[22:23], v5, v2
	v_cmp_lt_u32_e64 s[24:25], v5, v3
	v_sub_u32_e32 v5, v5, v32
	v_max_i32_e32 v5, -15, v5
	v_add_u32_e32 v5, 15, v5
	v_min_u32_e32 v106, 30, v5
	v_add_u32_e32 v5, 10, v4
	v_cmp_ge_u32_e64 s[26:27], v5, v2
	v_cmp_lt_u32_e64 s[28:29], v5, v3
	v_sub_u32_e32 v5, v5, v32
	v_max_i32_e32 v5, -15, v5
	v_add_u32_e32 v5, 15, v5
	v_min_u32_e32 v107, 30, v5
	v_add_u32_e32 v5, 11, v4
	v_cmp_ge_u32_e64 s[30:31], v5, v2
	v_cmp_lt_u32_e64 s[34:35], v5, v3
	v_sub_u32_e32 v5, v5, v32
	v_max_i32_e32 v5, -15, v5
	v_add_u32_e32 v5, 15, v5
	v_min_u32_e32 v108, 30, v5
	v_add_u32_e32 v5, 16, v4
	v_cmp_ge_u32_e64 s[36:37], v5, v2
	v_sub_u32_e32 v5, v5, v32
	v_max_i32_e32 v5, -15, v5
	v_add_u32_e32 v5, 15, v5
	v_min_u32_e32 v109, 30, v5
	v_add_u32_e32 v5, 17, v4
	v_cmp_ge_u32_e64 s[40:41], v5, v2
	v_cmp_lt_u32_e64 s[42:43], v5, v3
	v_sub_u32_e32 v5, v5, v32
	v_max_i32_e32 v5, -15, v5
	v_add_u32_e32 v5, 15, v5
	v_min_u32_e32 v110, 30, v5
	v_add_u32_e32 v5, 18, v4
	v_cmp_ge_u32_e64 s[44:45], v5, v2
	v_cmp_lt_u32_e64 s[46:47], v5, v3
	v_sub_u32_e32 v5, v5, v32
	v_max_i32_e32 v5, -15, v5
	v_add_u32_e32 v5, 15, v5
	v_min_u32_e32 v111, 30, v5
	v_add_u32_e32 v5, 19, v4
	v_cmp_ge_u32_e64 s[48:49], v5, v2
	v_cmp_lt_u32_e64 s[50:51], v5, v3
	v_sub_u32_e32 v5, v5, v32
	v_max_i32_e32 v5, -15, v5
	v_add_u32_e32 v5, 15, v5
	v_min_u32_e32 v112, 30, v5
	v_add_u32_e32 v5, 24, v4
	v_cmp_ge_u32_e64 s[52:53], v5, v2
	v_cmp_lt_u32_e64 s[54:55], v5, v3
	v_sub_u32_e32 v5, v5, v32
	v_max_i32_e32 v5, -15, v5
	v_add_u32_e32 v5, 15, v5
	v_mad_i32_i24 v0, v35, 10, v33
	v_min_u32_e32 v113, 30, v5
	v_add_u32_e32 v5, 25, v4
	v_ashrrev_i32_e32 v1, 31, v0
	v_cmp_ge_u32_e64 s[56:57], v5, v2
	v_cmp_lt_u32_e64 s[58:59], v5, v3
	v_sub_u32_e32 v5, v5, v32
	v_lshlrev_b64 v[0:1], 18, v[0:1]
	v_max_i32_e32 v5, -15, v5
	v_lshl_add_u64 v[0:1], v[66:67], 0, v[0:1]
	s_mov_b64 s[0:1], 0x20000
	v_add_u32_e32 v5, 15, v5
	v_lshl_add_u64 v[84:85], v[0:1], 0, s[0:1]
	v_cmp_ge_u32_e64 s[0:1], v4, v2
	v_cmp_lt_u32_e64 s[4:5], v4, v3
	v_cmp_lt_u32_e64 s[38:39], v4, v2
	v_min_u32_e32 v114, 30, v5
	v_add_u32_e32 v5, 26, v4
	v_add_u32_e32 v4, 27, v4
	v_cmp_ge_u32_e64 s[60:61], v5, v2
	v_cmp_lt_u32_e64 s[62:63], v5, v3
	v_sub_u32_e32 v5, v5, v32
	v_cmp_ge_u32_e64 s[64:65], v4, v2
	v_sub_u32_e32 v2, v4, v32
	v_max_i32_e32 v5, -15, v5
	v_max_i32_e32 v2, -15, v2
	v_writelane_b32 v254, s0, 61
	v_add_u32_e32 v5, 15, v5
	v_add_u32_e32 v2, 15, v2
	v_or_b32_e32 v99, v34, v90
	v_add_u32_e32 v100, 8, v98
	v_writelane_b32 v254, s1, 62
	v_min_u32_e32 v115, 30, v5
	v_cmp_lt_u32_e64 s[66:67], v4, v3
	v_min_u32_e32 v116, 30, v2
	v_lshl_add_u64 v[86:87], v[72:73], 0, v[82:83]
	v_lshl_add_u64 v[88:89], v[0:1], 0, v[78:79]
	s_mov_b32 s33, 0
	v_mov_b32_e32 v83, 0xf149f2ca
	s_mov_b64 s[0:1], 0
	v_mov_b32_e32 v0, 0
	v_mov_b32_e32 v1, v117
	v_mov_b32_e32 v2, v117
	v_mov_b32_e32 v3, v117
	v_mov_b32_e32 v4, v117
	v_mov_b32_e32 v5, v117
	v_mov_b32_e32 v6, v117
	v_mov_b32_e32 v7, v117
	v_mov_b32_e32 v8, v117
	v_mov_b32_e32 v9, v117
	v_mov_b32_e32 v10, v117
	v_mov_b32_e32 v11, v117
	v_mov_b32_e32 v12, v117
	v_mov_b32_e32 v13, v117
	v_mov_b32_e32 v14, v117
	v_mov_b32_e32 v15, v117
	v_mov_b32_e32 v16, 0
	v_mov_b32_e32 v17, v117
	v_mov_b32_e32 v18, v117
	v_mov_b32_e32 v19, v117
	v_mov_b32_e32 v20, v117
	v_mov_b32_e32 v21, v117
	v_mov_b32_e32 v22, v117
	v_mov_b32_e32 v23, v117
	v_mov_b32_e32 v24, v117
	v_mov_b32_e32 v25, v117
	v_mov_b32_e32 v26, v117
	v_mov_b32_e32 v27, v117
	v_mov_b32_e32 v28, v117
	v_mov_b32_e32 v29, v117
	v_mov_b32_e32 v30, v117
	v_mov_b32_e32 v31, v117
.LBB0_248:
	v_add_u32_e32 v32, s33, v96
	v_lshl_or_b32 v64, v32, 6, v75
	v_sub_u32_e32 v33, v32, v77
	v_cmp_ge_u32_e32 vcc, v32, v98
	v_cmp_lt_u32_e64 s[68:69], v32, v100
	v_add_u32_e32 v32, v99, v64
	v_max_i32_e32 v33, -7, v33
	v_mad_i64_i32 v[36:37], s[2:3], v32, s89, v[86:87]
	v_add_u32_e32 v38, 7, v33
	global_load_dwordx4 v[32:35], v[36:37], off offset:1024
	global_load_dwordx4 v[118:121], v[36:37], off offset:1056
	global_load_dwordx4 v[122:125], v[36:37], off offset:1088
	global_load_dwordx4 v[126:129], v[36:37], off offset:1120
	s_and_b64 s[84:85], vcc, s[68:69]
	v_min_u32_e32 v36, 14, v38
	s_movk_i32 vcc_lo, 0x7c
	v_mad_u32_u24 v130, v36, vcc_lo, v91
	v_lshl_add_u32 v160, v161, 2, v130
	ds_read_b32 v131, v160
	ds_read_b32 v132, v160 offset:4
	v_readlane_b32 s2, v254, 61
	v_readlane_b32 s3, v254, 62
	s_and_b64 s[2:3], s[84:85], s[2:3]
	s_and_b64 s[96:97], s[84:85], s[6:7]
	s_and_b64 s[94:95], s[84:85], s[10:11]
	s_and_b64 s[92:93], s[84:85], s[14:15]
	s_and_b64 s[96:97], s[96:97], s[8:9]
	s_and_b64 s[2:3], s[2:3], s[4:5]
	s_and_b64 s[90:91], s[84:85], s[18:19]
	s_and_b64 s[88:89], s[84:85], s[22:23]
	s_and_b64 s[94:95], s[94:95], s[12:13]
	s_and_b64 s[92:93], s[92:93], s[16:17]
	s_and_b64 s[86:87], s[84:85], s[26:27]
	s_and_b64 s[68:69], s[84:85], s[30:31]
	s_and_b64 s[90:91], s[90:91], s[20:21]
	s_and_b64 s[88:89], s[88:89], s[24:25]
	s_and_b64 s[70:71], s[84:85], s[36:37]
	s_and_b64 s[72:73], s[84:85], s[40:41]
	s_and_b64 s[86:87], s[86:87], s[28:29]
	s_and_b64 s[68:69], s[68:69], s[34:35]
	s_and_b64 s[74:75], s[84:85], s[44:45]
	s_and_b64 s[76:77], s[84:85], s[48:49]
	s_and_b64 s[70:71], s[70:71], s[38:39]
	s_and_b64 s[72:73], s[72:73], s[42:43]
	s_and_b64 s[78:79], s[84:85], s[52:53]
	s_and_b64 s[80:81], s[84:85], s[56:57]
	s_and_b64 s[74:75], s[74:75], s[46:47]
	s_and_b64 s[76:77], s[76:77], s[50:51]
	s_and_b64 s[82:83], s[84:85], s[60:61]
	s_and_b64 s[84:85], s[84:85], s[64:65]
	s_and_b64 s[78:79], s[78:79], s[54:55]
	s_and_b64 s[80:81], s[80:81], s[58:59]
	s_and_b64 s[82:83], s[82:83], s[62:63]
	s_and_b64 s[84:85], s[84:85], s[66:67]
	s_add_i32 s33, s33, 1
	v_cmp_ge_i32_e32 vcc, s33, v97
	s_or_b64 s[0:1], vcc, s[0:1]
	s_waitcnt vmcnt(3)
	v_mfma_f32_32x32x16_bf16 v[32:47], v[32:35], v[48:51], 0
	s_waitcnt vmcnt(2)
	v_mfma_f32_32x32x16_bf16 v[32:47], v[118:121], v[52:55], v[32:47]
	ds_read_b32 v118, v160 offset:8
	ds_read_b32 v119, v160 offset:12
	ds_read_b32 v120, v160 offset:32
	ds_read_b32 v121, v160 offset:36
	ds_read_b32 v133, v160 offset:40
	ds_read_b32 v134, v160 offset:44
	ds_read_b32 v135, v160 offset:64
	s_waitcnt vmcnt(1)
	v_mfma_f32_32x32x16_bf16 v[32:47], v[122:125], v[56:59], v[32:47]
	ds_read_b32 v122, v160 offset:68
	ds_read_b32 v123, v160 offset:72
	ds_read_b32 v124, v160 offset:76
	ds_read_b32 v125, v160 offset:96
	ds_read_b32 v136, v160 offset:100
	ds_read_b32 v137, v160 offset:104
	ds_read_b32 v130, v160 offset:108
	s_waitcnt vmcnt(0)
	v_mfma_f32_32x32x16_bf16 v[32:47], v[126:129], v[60:63], v[32:47]
	s_waitcnt lgkmcnt(14)
	s_nop 10
	v_add_f32_e32 v32, v32, v131
	v_add_f32_e32 v33, v33, v132
	s_waitcnt lgkmcnt(13)
	v_add_f32_e32 v34, v34, v118
	s_waitcnt lgkmcnt(12)
	v_add_f32_e32 v118, v35, v119
	v_max_f32_e32 v35, 0xf149f2ca, v32
	s_waitcnt lgkmcnt(11)
	v_add_f32_e32 v119, v36, v120
	v_cndmask_b32_e64 v36, v95, v33, s[96:97]
	v_cndmask_b32_e64 v35, v95, v35, s[2:3]
	s_waitcnt lgkmcnt(10)
	v_add_f32_e32 v120, v37, v121
	s_waitcnt lgkmcnt(9)
	v_add_f32_e32 v121, v38, v133
	v_cndmask_b32_e64 v37, v95, v34, s[94:95]
	v_cndmask_b32_e64 v38, v95, v118, s[92:93]
	v_max_f32_e32 v35, v35, v36
	s_waitcnt lgkmcnt(8)
	v_add_f32_e32 v126, v39, v134
	s_waitcnt lgkmcnt(7)
	v_add_f32_e32 v127, v40, v135
	v_cndmask_b32_e64 v39, v95, v119, s[90:91]
	v_cndmask_b32_e64 v40, v95, v120, s[88:89]
	v_max3_f32 v35, v35, v37, v38
	s_waitcnt lgkmcnt(6)
	v_add_f32_e32 v122, v41, v122
	s_waitcnt lgkmcnt(5)
	v_add_f32_e32 v123, v42, v123
	v_cndmask_b32_e64 v41, v95, v121, s[86:87]
	v_cndmask_b32_e64 v42, v95, v126, s[68:69]
	v_max3_f32 v35, v35, v39, v40
	s_waitcnt lgkmcnt(4)
	v_add_f32_e32 v124, v43, v124
	s_waitcnt lgkmcnt(3)
	v_add_f32_e32 v125, v44, v125
	v_cndmask_b32_e64 v43, v95, v127, s[70:71]
	v_cndmask_b32_e64 v44, v95, v122, s[72:73]
	v_max3_f32 v35, v35, v41, v42
	s_waitcnt lgkmcnt(2)
	v_add_f32_e32 v128, v45, v136
	s_waitcnt lgkmcnt(1)
	v_add_f32_e32 v129, v46, v137
	v_cndmask_b32_e64 v45, v95, v123, s[74:75]
	v_cndmask_b32_e64 v46, v95, v124, s[76:77]
	v_max3_f32 v35, v35, v43, v44
	s_waitcnt lgkmcnt(0)
	v_add_f32_e32 v130, v47, v130
	v_cndmask_b32_e64 v47, v95, v125, s[78:79]
	v_cndmask_b32_e64 v131, v95, v128, s[80:81]
	v_max3_f32 v35, v35, v45, v46
	v_cndmask_b32_e64 v132, v95, v129, s[82:83]
	v_cndmask_b32_e64 v133, v95, v130, s[84:85]
	v_max3_f32 v35, v35, v47, v131
	v_max3_f32 v35, v35, v132, v133
	v_mov_b32_e32 v36, v35
	s_nop 1
	v_permlane32_swap_b32_e32 v35, v36
	v_max3_f32 v131, v83, v35, v36
	v_sub_f32_e32 v32, v32, v131
	v_mul_f32_e32 v32, 0x3fb8aa3b, v32
	v_exp_f32_e32 v32, v32
	v_mov_b32_e32 v135, v117
	v_sub_f32_e32 v117, v118, v131
	v_sub_f32_e32 v118, v119, v131
	v_cndmask_b32_e64 v132, 0, v32, s[2:3]
	v_sub_f32_e32 v32, v33, v131
	v_mul_f32_e32 v32, 0x3fb8aa3b, v32
	v_exp_f32_e32 v32, v32
	v_sub_f32_e32 v119, v120, v131
	v_sub_f32_e32 v120, v121, v131
	v_sub_f32_e32 v121, v126, v131
	v_cndmask_b32_e64 v133, 0, v32, s[96:97]
	v_sub_f32_e32 v32, v34, v131
	v_mul_f32_e32 v32, 0x3fb8aa3b, v32
	v_exp_f32_e32 v32, v32
	v_mul_f32_e32 v117, 0x3fb8aa3b, v117
	v_mul_f32_e32 v118, 0x3fb8aa3b, v118
	v_mul_f32_e32 v119, 0x3fb8aa3b, v119
	v_cndmask_b32_e64 v134, 0, v32, s[94:95]
	v_lshlrev_b64 v[32:33], 1, v[64:65]
	v_lshl_add_u64 v[38:39], v[88:89], 0, v[32:33]
	v_lshl_add_u64 v[36:37], v[84:85], 0, v[32:33]
	global_load_dwordx2 v[32:33], v[38:39], off
	global_load_dwordx2 v[34:35], v[38:39], off offset:16
	v_lshl_add_u64 v[46:47], v[36:37], 0, v[78:79]
	global_load_dwordx2 v[36:37], v[38:39], off offset:32
	s_nop 0
	global_load_dwordx2 v[38:39], v[38:39], off offset:48
	s_nop 0
	global_load_dwordx2 v[40:41], v[46:47], off
	global_load_dwordx2 v[42:43], v[46:47], off offset:16
	global_load_dwordx2 v[44:45], v[46:47], off offset:32
	s_nop 0
	global_load_dwordx2 v[46:47], v[46:47], off offset:48
	v_sub_f32_e32 v64, v83, v131
	v_mul_f32_e32 v120, 0x3fb8aa3b, v120
	v_mul_f32_e32 v121, 0x3fb8aa3b, v121
	v_mul_f32_e32 v64, 0x3fb8aa3b, v64
	v_exp_f32_e32 v117, v117
	v_exp_f32_e32 v118, v118
	v_exp_f32_e32 v119, v119
	v_exp_f32_e32 v120, v120
	v_exp_f32_e32 v121, v121
	v_exp_f32_e32 v64, v64
	v_sub_f32_e32 v126, v127, v131
	v_sub_f32_e32 v122, v122, v131
	v_sub_f32_e32 v123, v123, v131
	v_sub_f32_e32 v124, v124, v131
	v_sub_f32_e32 v125, v125, v131
	v_sub_f32_e32 v127, v128, v131
	v_sub_f32_e32 v128, v129, v131
	v_sub_f32_e32 v129, v130, v131
	v_mov_b32_e32 v83, v131
	v_cndmask_b32_e64 v117, 0, v117, s[92:93]
	v_cndmask_b32_e64 v130, 0, v118, s[90:91]
	v_cndmask_b32_e64 v131, 0, v119, s[88:89]
	v_cndmask_b32_e64 v136, 0, v120, s[86:87]
	v_cndmask_b32_e64 v137, 0, v121, s[68:69]
	v_pk_mul_f32 v[14:15], v[14:15], v[64:65] op_sel_hi:[1,0]
	v_pk_mul_f32 v[12:13], v[12:13], v[64:65] op_sel_hi:[1,0]
	v_pk_mul_f32 v[10:11], v[10:11], v[64:65] op_sel_hi:[1,0]
	v_pk_mul_f32 v[8:9], v[8:9], v[64:65] op_sel_hi:[1,0]
	v_pk_mul_f32 v[6:7], v[6:7], v[64:65] op_sel_hi:[1,0]
	v_pk_mul_f32 v[4:5], v[4:5], v[64:65] op_sel_hi:[1,0]
	v_pk_mul_f32 v[2:3], v[2:3], v[64:65] op_sel_hi:[1,0]
	v_pk_mul_f32 v[0:1], v[0:1], v[64:65] op_sel_hi:[1,0]
	v_cvt_pk_bf16_f32 v118, v132, v133
	v_cvt_pk_bf16_f32 v119, v134, v117
	v_cvt_pk_bf16_f32 v120, v130, v131
	v_cvt_pk_bf16_f32 v121, v136, v137
	v_mul_f32_e32 v126, 0x3fb8aa3b, v126
	v_mul_f32_e32 v122, 0x3fb8aa3b, v122
	s_waitcnt vmcnt(6)
	v_mfma_f32_32x32x16_bf16 v[0:15], v[32:35], v[118:121], v[0:15]
	v_mul_f32_e32 v123, 0x3fb8aa3b, v123
	v_mul_f32_e32 v124, 0x3fb8aa3b, v124
	v_mul_f32_e32 v125, 0x3fb8aa3b, v125
	v_mul_f32_e32 v127, 0x3fb8aa3b, v127
	v_mul_f32_e32 v128, 0x3fb8aa3b, v128
	v_mul_f32_e32 v129, 0x3fb8aa3b, v129
	v_exp_f32_e32 v126, v126
	v_exp_f32_e32 v122, v122
	v_exp_f32_e32 v123, v123
	v_exp_f32_e32 v124, v124
	v_exp_f32_e32 v125, v125
	v_exp_f32_e32 v127, v127
	v_exp_f32_e32 v128, v128
	v_exp_f32_e32 v129, v129
	v_pk_mul_f32 v[30:31], v[30:31], v[64:65] op_sel_hi:[1,0]
	v_pk_mul_f32 v[28:29], v[28:29], v[64:65] op_sel_hi:[1,0]
	v_pk_mul_f32 v[26:27], v[26:27], v[64:65] op_sel_hi:[1,0]
	v_pk_mul_f32 v[24:25], v[24:25], v[64:65] op_sel_hi:[1,0]
	v_pk_mul_f32 v[22:23], v[22:23], v[64:65] op_sel_hi:[1,0]
	v_pk_mul_f32 v[20:21], v[20:21], v[64:65] op_sel_hi:[1,0]
	v_pk_mul_f32 v[18:19], v[18:19], v[64:65] op_sel_hi:[1,0]
	v_pk_mul_f32 v[16:17], v[16:17], v[64:65] op_sel_hi:[1,0]
	v_cndmask_b32_e64 v126, 0, v126, s[70:71]
	v_cndmask_b32_e64 v122, 0, v122, s[72:73]
	s_waitcnt vmcnt(2)
	v_mfma_f32_32x32x16_bf16 v[16:31], v[40:43], v[118:121], v[16:31]
	v_add_f32_e32 v40, 0, v132
	v_cndmask_b32_e64 v123, 0, v123, s[74:75]
	v_cndmask_b32_e64 v124, 0, v124, s[76:77]
	v_cndmask_b32_e64 v125, 0, v125, s[78:79]
	v_cndmask_b32_e64 v127, 0, v127, s[80:81]
	v_cndmask_b32_e64 v128, 0, v128, s[82:83]
	v_cndmask_b32_e64 v129, 0, v129, s[84:85]
	v_add_f32_e32 v40, v133, v40
	v_cvt_pk_bf16_f32 v32, v126, v122
	v_cvt_pk_bf16_f32 v33, v123, v124
	v_cvt_pk_bf16_f32 v34, v125, v127
	v_cvt_pk_bf16_f32 v35, v128, v129
	v_add_f32_e32 v40, v134, v40
	s_movk_i32 s89, 0x2200
	v_mfma_f32_32x32x16_bf16 v[0:15], v[36:39], v[32:35], v[0:15]
	v_add_f32_e32 v36, v117, v40
	v_add_f32_e32 v36, v130, v36
	v_add_f32_e32 v36, v131, v36
	v_add_f32_e32 v36, v136, v36
	v_add_f32_e32 v36, v137, v36
	v_add_f32_e32 v36, v126, v36
	v_add_f32_e32 v36, v122, v36
	s_waitcnt vmcnt(0)
	v_mfma_f32_32x32x16_bf16 v[16:31], v[44:47], v[32:35], v[16:31]
	v_add_f32_e32 v32, v123, v36
	v_add_f32_e32 v32, v124, v32
	v_add_f32_e32 v32, v125, v32
	v_add_f32_e32 v32, v127, v32
	v_add_f32_e32 v32, v128, v32
	v_add_f32_e32 v117, v129, v32
	v_fmac_f32_e32 v117, v135, v64
	s_andn2_b64 exec, exec, s[0:1]
	s_cbranch_execnz .LBB0_248
	s_or_b64 exec, exec, s[0:1]
	v_readlane_b32 s68, v254, 25
	v_readlane_b32 s72, v254, 29
	v_readlane_b32 s73, v254, 30
	v_readlane_b32 s70, v254, 27
	v_readlane_b32 s71, v254, 28
	v_readlane_b32 s82, v254, 39
	v_readlane_b32 s83, v254, 40
	v_readlane_b32 s90, v254, 45
	v_readlane_b32 s86, v254, 47
	v_readlane_b32 s72, v254, 51
	v_readlane_b32 s16, v254, 59
	v_readlane_b32 s20, v254, 53
	v_readlane_b32 s22, v254, 55
	v_readlane_b32 s2, v254, 57
	s_mov_b64 s[70:71], s[82:83]
	v_readlane_b32 s91, v254, 46
	s_mov_b32 s88, s86
	s_mov_b32 s84, s72
	v_readlane_b32 s17, v254, 60
	v_readlane_b32 s21, v254, 54
	v_readlane_b32 s23, v254, 56
	v_readlane_b32 s3, v254, 58
	v_readlane_b32 s69, v254, 26
	v_readlane_b32 s74, v254, 31
	v_readlane_b32 s75, v254, 32
	v_readlane_b32 s76, v254, 33
	v_readlane_b32 s77, v254, 34
	v_readlane_b32 s78, v254, 35
	v_readlane_b32 s79, v254, 36
	v_readlane_b32 s80, v254, 37
	v_readlane_b32 s81, v254, 38
	v_readlane_b32 s87, v254, 48
	v_readlane_b32 s73, v254, 52
	s_branch .LBB0_243

.LBB0_831:
	s_or_b64 exec, exec, s[0:1]
	v_lshrrev_b32_e32 v0, 3, v69
	v_and_b32_e32 v1, 4, v69
	v_and_or_b32 v0, v0, 56, v1
	v_lshrrev_b32_e32 v0, 1, v0
	v_or_b32_e32 v87, v0, v106
	v_lshlrev_b32_e32 v1, 4, v69
	v_sub_u32_e64 v2, v0, 4 clamp
	v_sub_u32_e64 v0, v0, 3 clamp
	v_and_b32_e32 v36, 48, v1
	v_ashrrev_i32_e32 v35, 9, v69
	v_min_u32_e32 v91, 24, v2
	v_min_u32_e32 v0, 24, v0
	v_or_b32_e32 v32, v36, v107
	v_lshlrev_b32_e32 v1, 6, v87
	v_lshlrev_b32_e32 v34, 11, v35
	v_sub_u32_e32 v0, v0, v91
	v_or3_b32 v94, v1, v34, v32
	v_lshlrev_b32_e32 v1, 6, v33
	v_add_u32_e32 v110, 8, v0
	v_mov_b32_e32 v15, 0
	v_ashrrev_i32_e32 v95, 31, v94
	v_cmp_lt_i32_e32 vcc, 0, v110
	v_lshlrev_b32_e32 v96, 1, v1
	v_mov_b32_e32 v14, v15
	v_mov_b32_e32 v13, v15
	v_mov_b32_e32 v12, v15
	v_mov_b32_e32 v11, v15
	v_mov_b32_e32 v10, v15
	v_mov_b32_e32 v9, v15
	v_mov_b32_e32 v8, v15
	v_mov_b32_e32 v7, v15
	v_mov_b32_e32 v6, v15
	v_mov_b32_e32 v5, v15
	v_mov_b32_e32 v4, v15
	v_mov_b32_e32 v3, v15
	v_mov_b32_e32 v2, v15
	v_mov_b32_e32 v1, v15
	v_mov_b32_e32 v0, v15
	v_mov_b32_e32 v31, v15
	v_mov_b32_e32 v30, v15
	v_mov_b32_e32 v29, v15
	v_mov_b32_e32 v28, v15
	v_mov_b32_e32 v27, v15
	v_mov_b32_e32 v26, v15
	v_mov_b32_e32 v25, v15
	v_mov_b32_e32 v24, v15
	v_mov_b32_e32 v23, v15
	v_mov_b32_e32 v22, v15
	v_mov_b32_e32 v21, v15
	v_mov_b32_e32 v20, v15
	v_mov_b32_e32 v19, v15
	v_mov_b32_e32 v18, v15
	v_mov_b32_e32 v17, v15
	v_mov_b32_e32 v16, v15
	v_mov_b32_e32 v130, v15
	s_waitcnt lgkmcnt(0)
	s_and_saveexec_b64 s[2:3], vcc
	s_cbranch_execz .LBB0_828
	v_writelane_b32 v254, s2, 57
	v_max_i32_e32 v0, 4, v87
	v_add_u32_e32 v3, -4, v0
	v_writelane_b32 v254, s3, 58
	v_writelane_b32 v254, s16, 59
	v_mov_b32_e32 v97, v65
	v_mov_b32_e32 v89, v65
	v_writelane_b32 v254, s17, 60
	v_sub_u32_e64 v2, v36, 8 clamp
	v_readlane_b32 s0, v254, 55
	v_readlane_b32 s1, v254, 56
	v_min_u32_e32 v111, 24, v3
	v_mov_b32_e32 v130, 0
	v_mov_b64_e32 v[0:1], s[0:1]
	v_mad_i64_i32 v[0:1], s[0:1], v94, s85, v[0:1]
	v_lshl_add_u64 v[0:1], v[0:1], 0, v[96:97]
	v_lshl_add_u64 v[0:1], v[0:1], 0, v[88:89]
	global_load_dwordx4 v[48:51], v[0:1], off
	global_load_dwordx4 v[52:55], v[0:1], off offset:32
	global_load_dwordx4 v[56:59], v[0:1], off offset:64
	global_load_dwordx4 v[60:63], v[0:1], off offset:96
	v_min_u32_e32 v89, 32, v2
	v_or_b32_e32 v4, v89, v68
	v_max_i32_e32 v2, 8, v32
	v_sub_u32_e32 v5, v4, v32
	v_add_u32_e32 v161, 15, v5
	v_add_u32_e32 v2, -8, v2
	v_max_i32_e32 v5, -15, v5
	v_min_u32_e32 v2, 48, v2
	v_add_u32_e32 v5, 15, v5
	v_add_u32_e32 v3, 16, v2
	v_min_u32_e32 v114, 30, v5
	v_or_b32_e32 v5, 1, v4
	v_cmp_ge_u32_e64 s[8:9], v5, v2
	v_cmp_lt_u32_e64 s[10:11], v5, v3
	v_sub_u32_e32 v5, v5, v32
	v_max_i32_e32 v5, -15, v5
	v_add_u32_e32 v5, 15, v5
	v_min_u32_e32 v115, 30, v5
	v_or_b32_e32 v5, 2, v4
	v_cmp_ge_u32_e64 s[12:13], v5, v2
	v_cmp_lt_u32_e64 s[14:15], v5, v3
	v_sub_u32_e32 v5, v5, v32
	v_max_i32_e32 v5, -15, v5
	v_add_u32_e32 v5, 15, v5
	v_min_u32_e32 v116, 30, v5
	v_or_b32_e32 v5, 3, v4
	v_cmp_ge_u32_e64 s[16:17], v5, v2
	v_cmp_lt_u32_e64 s[18:19], v5, v3
	v_sub_u32_e32 v5, v5, v32
	v_max_i32_e32 v5, -15, v5
	v_add_u32_e32 v5, 15, v5
	v_min_u32_e32 v117, 30, v5
	v_add_u32_e32 v5, 8, v4
	v_cmp_ge_u32_e64 s[20:21], v5, v2
	v_cmp_lt_u32_e64 s[22:23], v5, v3
	v_sub_u32_e32 v5, v5, v32
	v_max_i32_e32 v5, -15, v5
	v_add_u32_e32 v5, 15, v5
	v_min_u32_e32 v118, 30, v5
	v_add_u32_e32 v5, 9, v4
	v_cmp_ge_u32_e64 s[24:25], v5, v2
	v_cmp_lt_u32_e64 s[26:27], v5, v3
	v_sub_u32_e32 v5, v5, v32
	v_max_i32_e32 v5, -15, v5
	v_add_u32_e32 v5, 15, v5
	v_min_u32_e32 v119, 30, v5
	v_add_u32_e32 v5, 10, v4
	v_cmp_ge_u32_e64 s[28:29], v5, v2
	v_cmp_lt_u32_e64 s[30:31], v5, v3
	v_sub_u32_e32 v5, v5, v32
	v_max_i32_e32 v5, -15, v5
	v_add_u32_e32 v5, 15, v5
	v_min_u32_e32 v120, 30, v5
	v_add_u32_e32 v5, 11, v4
	v_cmp_ge_u32_e64 s[34:35], v5, v2
	v_cmp_lt_u32_e64 s[36:37], v5, v3
	v_sub_u32_e32 v5, v5, v32
	v_max_i32_e32 v5, -15, v5
	v_add_u32_e32 v5, 15, v5
	v_min_u32_e32 v121, 30, v5
	v_add_u32_e32 v5, 16, v4
	v_cmp_ge_u32_e64 s[38:39], v5, v2
	v_sub_u32_e32 v5, v5, v32
	v_max_i32_e32 v5, -15, v5
	v_add_u32_e32 v5, 15, v5
	v_min_u32_e32 v122, 30, v5
	v_add_u32_e32 v5, 17, v4
	v_cmp_ge_u32_e64 s[42:43], v5, v2
	v_cmp_lt_u32_e64 s[44:45], v5, v3
	v_sub_u32_e32 v5, v5, v32
	v_max_i32_e32 v5, -15, v5
	v_add_u32_e32 v5, 15, v5
	v_min_u32_e32 v123, 30, v5
	v_add_u32_e32 v5, 18, v4
	v_cmp_ge_u32_e64 s[46:47], v5, v2
	v_cmp_lt_u32_e64 s[48:49], v5, v3
	v_sub_u32_e32 v5, v5, v32
	v_max_i32_e32 v5, -15, v5
	v_add_u32_e32 v5, 15, v5
	v_min_u32_e32 v124, 30, v5
	v_add_u32_e32 v5, 19, v4
	v_cmp_ge_u32_e64 s[50:51], v5, v2
	v_cmp_lt_u32_e64 s[52:53], v5, v3
	v_sub_u32_e32 v5, v5, v32
	v_max_i32_e32 v5, -15, v5
	v_add_u32_e32 v5, 15, v5
	v_min_u32_e32 v125, 30, v5
	v_add_u32_e32 v5, 24, v4
	v_cmp_ge_u32_e64 s[54:55], v5, v2
	v_cmp_lt_u32_e64 s[56:57], v5, v3
	v_sub_u32_e32 v5, v5, v32
	v_max_i32_e32 v5, -15, v5
	v_add_u32_e32 v5, 15, v5
	v_mad_i32_i24 v0, v35, 10, v33
	v_min_u32_e32 v126, 30, v5
	v_add_u32_e32 v5, 25, v4
	v_ashrrev_i32_e32 v1, 31, v0
	v_cmp_ge_u32_e64 s[58:59], v5, v2
	v_cmp_lt_u32_e64 s[60:61], v5, v3
	v_sub_u32_e32 v5, v5, v32
	v_lshlrev_b64 v[0:1], 18, v[0:1]
	v_max_i32_e32 v5, -15, v5
	v_lshl_add_u64 v[0:1], v[66:67], 0, v[0:1]
	s_mov_b64 s[0:1], 0x20000
	v_add_u32_e32 v5, 15, v5
	v_lshl_add_u64 v[98:99], v[0:1], 0, s[0:1]
	v_cmp_ge_u32_e64 s[0:1], v4, v2
	v_cmp_lt_u32_e64 s[6:7], v4, v3
	v_cmp_lt_u32_e64 s[40:41], v4, v2
	v_min_u32_e32 v127, 30, v5
	v_add_u32_e32 v5, 26, v4
	v_add_u32_e32 v4, 27, v4
	v_cmp_ge_u32_e64 s[62:63], v5, v2
	v_cmp_lt_u32_e64 s[64:65], v5, v3
	v_sub_u32_e32 v5, v5, v32
	v_cmp_ge_u32_e64 s[66:67], v4, v2
	v_sub_u32_e32 v2, v4, v32
	v_max_i32_e32 v5, -15, v5
	v_max_i32_e32 v2, -15, v2
	v_writelane_b32 v254, s0, 61
	v_add_u32_e32 v5, 15, v5
	v_add_u32_e32 v2, 15, v2
	v_or_b32_e32 v112, v34, v104
	v_add_u32_e32 v113, 8, v111
	v_writelane_b32 v254, s1, 62
	v_min_u32_e32 v128, 30, v5
	v_cmp_lt_u32_e64 s[68:69], v4, v3
	v_min_u32_e32 v129, 30, v2
	v_lshl_add_u64 v[100:101], v[70:71], 0, v[96:97]
	v_lshl_add_u64 v[102:103], v[0:1], 0, v[92:93]
	s_mov_b32 s33, 0
	v_mov_b32_e32 v97, 0xf149f2ca
	s_mov_b64 s[0:1], 0
	v_mov_b32_e32 v0, 0
	v_mov_b32_e32 v1, v130
	v_mov_b32_e32 v2, v130
	v_mov_b32_e32 v3, v130
	v_mov_b32_e32 v4, v130
	v_mov_b32_e32 v5, v130
	v_mov_b32_e32 v6, v130
	v_mov_b32_e32 v7, v130
	v_mov_b32_e32 v8, v130
	v_mov_b32_e32 v9, v130
	v_mov_b32_e32 v10, v130
	v_mov_b32_e32 v11, v130
	v_mov_b32_e32 v12, v130
	v_mov_b32_e32 v13, v130
	v_mov_b32_e32 v14, v130
	v_mov_b32_e32 v15, v130
	v_mov_b32_e32 v16, 0
	v_mov_b32_e32 v17, v130
	v_mov_b32_e32 v18, v130
	v_mov_b32_e32 v19, v130
	v_mov_b32_e32 v20, v130
	v_mov_b32_e32 v21, v130
	v_mov_b32_e32 v22, v130
	v_mov_b32_e32 v23, v130
	v_mov_b32_e32 v24, v130
	v_mov_b32_e32 v25, v130
	v_mov_b32_e32 v26, v130
	v_mov_b32_e32 v27, v130
	v_mov_b32_e32 v28, v130
	v_mov_b32_e32 v29, v130
	v_mov_b32_e32 v30, v130
	v_mov_b32_e32 v31, v130
.LBB0_833:
	v_add_u32_e32 v32, s33, v91
	v_lshl_or_b32 v64, v32, 6, v89
	v_sub_u32_e32 v33, v32, v87
	v_cmp_ge_u32_e32 vcc, v32, v111
	v_cmp_lt_u32_e64 s[2:3], v32, v113
	v_add_u32_e32 v32, v112, v64
	v_max_i32_e32 v33, -7, v33
	s_and_b64 s[86:87], vcc, s[2:3]
	v_mad_i64_i32 v[36:37], s[2:3], v32, s85, v[100:101]
	v_add_u32_e32 v38, 7, v33
	global_load_dwordx4 v[32:35], v[36:37], off offset:1024
	global_load_dwordx4 v[132:135], v[36:37], off offset:1056
	global_load_dwordx4 v[136:139], v[36:37], off offset:1088
	global_load_dwordx4 v[140:143], v[36:37], off offset:1120
	v_min_u32_e32 v36, 14, v38
	s_movk_i32 vcc_lo, 0x7c
	v_mad_u32_u24 v131, v36, vcc_lo, v105
	v_lshl_add_u32 v160, v161, 2, v131
	ds_read_b32 v144, v160
	ds_read_b32 v145, v160 offset:4
	v_readlane_b32 s2, v254, 61
	v_readlane_b32 s3, v254, 62
	s_and_b64 s[2:3], s[86:87], s[2:3]
	s_and_b64 s[4:5], s[86:87], s[8:9]
	s_and_b64 s[96:97], s[86:87], s[12:13]
	s_and_b64 s[94:95], s[86:87], s[16:17]
	s_and_b64 s[4:5], s[4:5], s[10:11]
	s_and_b64 s[2:3], s[2:3], s[6:7]
	s_and_b64 s[92:93], s[86:87], s[20:21]
	s_and_b64 s[90:91], s[86:87], s[24:25]
	s_and_b64 s[96:97], s[96:97], s[14:15]
	s_and_b64 s[94:95], s[94:95], s[18:19]
	s_and_b64 s[88:89], s[86:87], s[28:29]
	s_and_b64 s[70:71], s[86:87], s[34:35]
	s_and_b64 s[92:93], s[92:93], s[22:23]
	s_and_b64 s[90:91], s[90:91], s[26:27]
	s_and_b64 s[72:73], s[86:87], s[38:39]
	s_and_b64 s[74:75], s[86:87], s[42:43]
	s_and_b64 s[88:89], s[88:89], s[30:31]
	s_and_b64 s[70:71], s[70:71], s[36:37]
	s_and_b64 s[76:77], s[86:87], s[46:47]
	s_and_b64 s[78:79], s[86:87], s[50:51]
	s_and_b64 s[72:73], s[72:73], s[40:41]
	s_and_b64 s[74:75], s[74:75], s[44:45]
	s_and_b64 s[80:81], s[86:87], s[54:55]
	s_and_b64 s[82:83], s[86:87], s[58:59]
	s_and_b64 s[76:77], s[76:77], s[48:49]
	s_and_b64 s[78:79], s[78:79], s[52:53]
	s_and_b64 s[84:85], s[86:87], s[62:63]
	s_and_b64 s[86:87], s[86:87], s[66:67]
	s_and_b64 s[80:81], s[80:81], s[56:57]
	s_and_b64 s[82:83], s[82:83], s[60:61]
	s_and_b64 s[84:85], s[84:85], s[64:65]
	s_and_b64 s[86:87], s[86:87], s[68:69]
	s_add_i32 s33, s33, 1
	v_cmp_ge_i32_e32 vcc, s33, v110
	s_or_b64 s[0:1], vcc, s[0:1]
	s_waitcnt vmcnt(3)
	v_mfma_f32_32x32x16_bf16 v[32:47], v[32:35], v[48:51], 0
	s_waitcnt vmcnt(2)
	v_mfma_f32_32x32x16_bf16 v[32:47], v[132:135], v[52:55], v[32:47]
	ds_read_b32 v132, v160 offset:8
	ds_read_b32 v133, v160 offset:12
	ds_read_b32 v134, v160 offset:32
	ds_read_b32 v135, v160 offset:36
	ds_read_b32 v146, v160 offset:40
	ds_read_b32 v147, v160 offset:44
	ds_read_b32 v148, v160 offset:64
	s_waitcnt vmcnt(1)
	v_mfma_f32_32x32x16_bf16 v[32:47], v[136:139], v[56:59], v[32:47]
	ds_read_b32 v136, v160 offset:68
	ds_read_b32 v137, v160 offset:72
	ds_read_b32 v138, v160 offset:76
	ds_read_b32 v139, v160 offset:96
	ds_read_b32 v149, v160 offset:100
	ds_read_b32 v150, v160 offset:104
	ds_read_b32 v131, v160 offset:108
	s_waitcnt vmcnt(0)
	v_mfma_f32_32x32x16_bf16 v[32:47], v[140:143], v[60:63], v[32:47]
	s_waitcnt lgkmcnt(14)
	s_nop 10
	v_add_f32_e32 v32, v32, v144
	v_add_f32_e32 v33, v33, v145
	s_waitcnt lgkmcnt(13)
	v_add_f32_e32 v34, v34, v132
	s_waitcnt lgkmcnt(12)
	v_add_f32_e32 v132, v35, v133
	v_max_f32_e32 v35, 0xf149f2ca, v32
	s_waitcnt lgkmcnt(11)
	v_add_f32_e32 v133, v36, v134
	v_cndmask_b32_e64 v36, v109, v33, s[4:5]
	v_cndmask_b32_e64 v35, v109, v35, s[2:3]
	s_waitcnt lgkmcnt(10)
	v_add_f32_e32 v134, v37, v135
	s_waitcnt lgkmcnt(9)
	v_add_f32_e32 v135, v38, v146
	v_cndmask_b32_e64 v37, v109, v34, s[96:97]
	v_cndmask_b32_e64 v38, v109, v132, s[94:95]
	v_max_f32_e32 v35, v35, v36
	s_waitcnt lgkmcnt(8)
	v_add_f32_e32 v140, v39, v147
	s_waitcnt lgkmcnt(7)
	v_add_f32_e32 v141, v40, v148
	v_cndmask_b32_e64 v39, v109, v133, s[92:93]
	v_cndmask_b32_e64 v40, v109, v134, s[90:91]
	v_max3_f32 v35, v35, v37, v38
	s_waitcnt lgkmcnt(6)
	v_add_f32_e32 v136, v41, v136
	s_waitcnt lgkmcnt(5)
	v_add_f32_e32 v137, v42, v137
	v_cndmask_b32_e64 v41, v109, v135, s[88:89]
	v_cndmask_b32_e64 v42, v109, v140, s[70:71]
	v_max3_f32 v35, v35, v39, v40
	s_waitcnt lgkmcnt(4)
	v_add_f32_e32 v138, v43, v138
	s_waitcnt lgkmcnt(3)
	v_add_f32_e32 v139, v44, v139
	v_cndmask_b32_e64 v43, v109, v141, s[72:73]
	v_cndmask_b32_e64 v44, v109, v136, s[74:75]
	v_max3_f32 v35, v35, v41, v42
	s_waitcnt lgkmcnt(2)
	v_add_f32_e32 v142, v45, v149
	s_waitcnt lgkmcnt(1)
	v_add_f32_e32 v143, v46, v150
	v_cndmask_b32_e64 v45, v109, v137, s[76:77]
	v_cndmask_b32_e64 v46, v109, v138, s[78:79]
	v_max3_f32 v35, v35, v43, v44
	s_waitcnt lgkmcnt(0)
	v_add_f32_e32 v131, v47, v131
	v_cndmask_b32_e64 v47, v109, v139, s[80:81]
	v_cndmask_b32_e64 v144, v109, v142, s[82:83]
	v_max3_f32 v35, v35, v45, v46
	v_cndmask_b32_e64 v145, v109, v143, s[84:85]
	v_cndmask_b32_e64 v146, v109, v131, s[86:87]
	v_max3_f32 v35, v35, v47, v144
	v_max3_f32 v35, v35, v145, v146
	v_mov_b32_e32 v36, v35
	s_nop 1
	v_permlane32_swap_b32_e32 v35, v36
	v_max3_f32 v144, v97, v35, v36
	v_sub_f32_e32 v32, v32, v144
	v_mul_f32_e32 v32, 0x3fb8aa3b, v32
	v_exp_f32_e32 v32, v32
	v_mov_b32_e32 v148, v130
	v_sub_f32_e32 v130, v132, v144
	v_sub_f32_e32 v132, v133, v144
	v_cndmask_b32_e64 v145, 0, v32, s[2:3]
	v_sub_f32_e32 v32, v33, v144
	v_mul_f32_e32 v32, 0x3fb8aa3b, v32
	v_exp_f32_e32 v32, v32
	v_sub_f32_e32 v133, v134, v144
	v_sub_f32_e32 v134, v135, v144
	v_sub_f32_e32 v135, v140, v144
	v_cndmask_b32_e64 v146, 0, v32, s[4:5]
	v_sub_f32_e32 v32, v34, v144
	v_mul_f32_e32 v32, 0x3fb8aa3b, v32
	v_exp_f32_e32 v32, v32
	v_sub_f32_e32 v131, v131, v144
	v_mul_f32_e32 v130, 0x3fb8aa3b, v130
	v_mul_f32_e32 v132, 0x3fb8aa3b, v132
	v_cndmask_b32_e64 v147, 0, v32, s[96:97]
	v_lshlrev_b64 v[32:33], 1, v[64:65]
	v_lshl_add_u64 v[38:39], v[102:103], 0, v[32:33]
	v_lshl_add_u64 v[36:37], v[98:99], 0, v[32:33]
	global_load_dwordx2 v[32:33], v[38:39], off
	global_load_dwordx2 v[34:35], v[38:39], off offset:16
	v_lshl_add_u64 v[46:47], v[36:37], 0, v[92:93]
	global_load_dwordx2 v[36:37], v[38:39], off offset:32
	s_nop 0
	global_load_dwordx2 v[38:39], v[38:39], off offset:48
	s_nop 0
	global_load_dwordx2 v[40:41], v[46:47], off
	global_load_dwordx2 v[42:43], v[46:47], off offset:16
	global_load_dwordx2 v[44:45], v[46:47], off offset:32
	s_nop 0
	global_load_dwordx2 v[46:47], v[46:47], off offset:48
	v_sub_f32_e32 v64, v97, v144
	v_mul_f32_e32 v133, 0x3fb8aa3b, v133
	v_mul_f32_e32 v134, 0x3fb8aa3b, v134
	v_mul_f32_e32 v135, 0x3fb8aa3b, v135
	v_mul_f32_e32 v64, 0x3fb8aa3b, v64
	v_mul_f32_e32 v131, 0x3fb8aa3b, v131
	v_exp_f32_e32 v130, v130
	v_exp_f32_e32 v132, v132
	v_exp_f32_e32 v133, v133
	v_exp_f32_e32 v134, v134
	v_exp_f32_e32 v135, v135
	v_exp_f32_e32 v131, v131
	v_exp_f32_e32 v64, v64
	v_sub_f32_e32 v140, v141, v144
	v_sub_f32_e32 v136, v136, v144
	v_sub_f32_e32 v137, v137, v144
	v_sub_f32_e32 v138, v138, v144
	v_sub_f32_e32 v139, v139, v144
	v_sub_f32_e32 v141, v142, v144
	v_sub_f32_e32 v142, v143, v144
	v_mov_b32_e32 v97, v144
	v_cndmask_b32_e64 v143, 0, v130, s[94:95]
	v_cndmask_b32_e64 v144, 0, v132, s[92:93]
	v_cndmask_b32_e64 v149, 0, v133, s[90:91]
	v_cndmask_b32_e64 v134, 0, v134, s[88:89]
	v_cndmask_b32_e64 v135, 0, v135, s[70:71]
	v_cndmask_b32_e64 v150, 0, v131, s[86:87]
	v_pk_mul_f32 v[14:15], v[14:15], v[64:65] op_sel_hi:[1,0]
	v_pk_mul_f32 v[12:13], v[12:13], v[64:65] op_sel_hi:[1,0]
	v_pk_mul_f32 v[10:11], v[10:11], v[64:65] op_sel_hi:[1,0]
	v_pk_mul_f32 v[8:9], v[8:9], v[64:65] op_sel_hi:[1,0]
	v_pk_mul_f32 v[6:7], v[6:7], v[64:65] op_sel_hi:[1,0]
	v_pk_mul_f32 v[4:5], v[4:5], v[64:65] op_sel_hi:[1,0]
	v_pk_mul_f32 v[2:3], v[2:3], v[64:65] op_sel_hi:[1,0]
	v_pk_mul_f32 v[0:1], v[0:1], v[64:65] op_sel_hi:[1,0]
	v_cvt_pk_bf16_f32 v130, v145, v146
	v_cvt_pk_bf16_f32 v131, v147, v143
	v_cvt_pk_bf16_f32 v132, v144, v149
	v_cvt_pk_bf16_f32 v133, v134, v135
	v_mul_f32_e32 v140, 0x3fb8aa3b, v140
	v_mul_f32_e32 v136, 0x3fb8aa3b, v136
	s_waitcnt vmcnt(6)
	v_mfma_f32_32x32x16_bf16 v[0:15], v[32:35], v[130:133], v[0:15]
	v_mul_f32_e32 v137, 0x3fb8aa3b, v137
	v_mul_f32_e32 v138, 0x3fb8aa3b, v138
	v_mul_f32_e32 v139, 0x3fb8aa3b, v139
	v_mul_f32_e32 v141, 0x3fb8aa3b, v141
	v_mul_f32_e32 v142, 0x3fb8aa3b, v142
	v_exp_f32_e32 v140, v140
	v_exp_f32_e32 v136, v136
	v_exp_f32_e32 v137, v137
	v_exp_f32_e32 v138, v138
	v_exp_f32_e32 v139, v139
	v_exp_f32_e32 v141, v141
	v_exp_f32_e32 v142, v142
	v_pk_mul_f32 v[30:31], v[30:31], v[64:65] op_sel_hi:[1,0]
	v_pk_mul_f32 v[28:29], v[28:29], v[64:65] op_sel_hi:[1,0]
	v_pk_mul_f32 v[26:27], v[26:27], v[64:65] op_sel_hi:[1,0]
	v_pk_mul_f32 v[24:25], v[24:25], v[64:65] op_sel_hi:[1,0]
	v_pk_mul_f32 v[22:23], v[22:23], v[64:65] op_sel_hi:[1,0]
	v_pk_mul_f32 v[20:21], v[20:21], v[64:65] op_sel_hi:[1,0]
	v_pk_mul_f32 v[18:19], v[18:19], v[64:65] op_sel_hi:[1,0]
	v_pk_mul_f32 v[16:17], v[16:17], v[64:65] op_sel_hi:[1,0]
	v_cndmask_b32_e64 v140, 0, v140, s[72:73]
	v_cndmask_b32_e64 v136, 0, v136, s[74:75]
	s_waitcnt vmcnt(2)
	v_mfma_f32_32x32x16_bf16 v[16:31], v[40:43], v[130:133], v[16:31]
	v_add_f32_e32 v40, 0, v145
	v_cndmask_b32_e64 v137, 0, v137, s[76:77]
	v_cndmask_b32_e64 v138, 0, v138, s[78:79]
	v_cndmask_b32_e64 v139, 0, v139, s[80:81]
	v_cndmask_b32_e64 v141, 0, v141, s[82:83]
	v_cndmask_b32_e64 v142, 0, v142, s[84:85]
	v_add_f32_e32 v40, v146, v40
	v_cvt_pk_bf16_f32 v32, v140, v136
	v_cvt_pk_bf16_f32 v33, v137, v138
	v_cvt_pk_bf16_f32 v34, v139, v141
	v_cvt_pk_bf16_f32 v35, v142, v150
	v_add_f32_e32 v40, v147, v40
	s_movk_i32 s85, 0x2200
	v_mfma_f32_32x32x16_bf16 v[0:15], v[36:39], v[32:35], v[0:15]
	v_add_f32_e32 v36, v143, v40
	v_add_f32_e32 v36, v144, v36
	v_add_f32_e32 v36, v149, v36
	v_add_f32_e32 v36, v134, v36
	v_add_f32_e32 v36, v135, v36
	v_add_f32_e32 v36, v140, v36
	v_add_f32_e32 v36, v136, v36
	s_waitcnt vmcnt(0)
	v_mfma_f32_32x32x16_bf16 v[16:31], v[44:47], v[32:35], v[16:31]
	v_add_f32_e32 v32, v137, v36
	v_add_f32_e32 v32, v138, v32
	v_add_f32_e32 v32, v139, v32
	v_add_f32_e32 v32, v141, v32
	v_add_f32_e32 v32, v142, v32
	v_add_f32_e32 v130, v150, v32
	v_fmac_f32_e32 v130, v148, v64
	s_andn2_b64 exec, exec, s[0:1]
	s_cbranch_execnz .LBB0_833
	s_or_b64 exec, exec, s[0:1]
	v_readlane_b32 s68, v254, 25
	v_readlane_b32 s72, v254, 29
	v_readlane_b32 s73, v254, 30
	v_readlane_b32 s88, v254, 47
	v_readlane_b32 s70, v254, 27
	v_readlane_b32 s71, v254, 28
	v_readlane_b32 s82, v254, 39
	v_readlane_b32 s83, v254, 40
	v_readlane_b32 s90, v254, 45
	v_readlane_b32 s89, v254, 48
	v_readlane_b32 s72, v254, 51
	v_readlane_b32 s92, v254, 53
	v_readlane_b32 s16, v254, 59
	v_readlane_b32 s18, v254, 41
	v_readlane_b32 s20, v254, 43
	v_readlane_b32 s2, v254, 57
	s_mov_b64 s[70:71], s[82:83]
	v_readlane_b32 s91, v254, 46
	s_mov_b32 s84, s72
	v_readlane_b32 s89, v254, 49
	v_readlane_b32 s93, v254, 54
	v_readlane_b32 s17, v254, 60
	v_readlane_b32 s19, v254, 42
	v_readlane_b32 s21, v254, 44
	v_readlane_b32 s3, v254, 58
	v_readlane_b32 s69, v254, 26
	v_readlane_b32 s74, v254, 31
	v_readlane_b32 s75, v254, 32
	v_readlane_b32 s76, v254, 33
	v_readlane_b32 s77, v254, 34
	v_readlane_b32 s78, v254, 35
	v_readlane_b32 s79, v254, 36
	v_readlane_b32 s80, v254, 37
	v_readlane_b32 s81, v254, 38
	v_readlane_b32 s73, v254, 52
	s_branch .LBB0_828
